# P3 mid: full-XCC poll issued after the gate loads (round trip overlaps their latency)
# baseline (speedup 1.0000x reference)
; #define GAS __attribute__((address_space(1)))
; __device__ __forceinline__ unsigned xb_ld(unsigned* p)              { return __hip_atomic_load(p, __ATOMIC_RELAXED, __HIP_MEMORY_SCOPE_AGENT); }
; #define XB_SPIN(cond, bar) do { unsigned _sp = 0; while (cond) { __builtin_amdgcn_s_sleep(1); \
;     if ((++_sp & 255u) == 0u) { if (xb_ld(&(bar)[XB_TMO])) break; if (_sp > XB_SPIN_CAP) { atomicAdd(&(bar)[XB_TMO], 1u); break; } } } } while (0)
; __device__ __forceinline__ bool is_t0(int wave) { return wave == 0 && olane() == 0; }
; __device__ __forceinline__ void xcdl_wait_t0(const XcdBarrier& b) {
;     if (is_t0(b.wave)) {
;         unsigned* bar = b.bar; asm volatile("" : "+s"(bar));
;         const unsigned gen = b.st[5];
;         XB_SPIN(xb_ld(&bar[XB_LGEN(b.x)]) == gen, bar);
;         __builtin_amdgcn_fence(__ATOMIC_ACQUIRE, "agent");
;         asm volatile("s_waitcnt vmcnt(0)" ::: "memory");
;     }
; }
;     __device__ __forceinline__ void mid(Acc& acc, const GUnit& u, int wr, int wc, int fr, int fq) const {
;         const int wl = ((wr * 4 + wc) * 64 + fq * 16 + fr) * 32;
;         const int bra = (u.kind == 0) ? 2 : u.kind - 1, brb = u.kind;
;         const unsigned char* Ga = MG8 + ((size_t)u.pm * 12 + bra * 4 + u.pn) * 65536 + wl; const unsigned char* Gb = MG8 + ((size_t)u.pm * 12 + brb * 4 + u.pn) * 65536 + wl;
; #pragma unroll
;         for (int ai = 0; ai < 2; ++ai)
; #pragma unroll
;             for (int bj = 0; bj < 2; ++bj) {
;                 const u32x4 a0 = *(const GAS u32x4*)(Ga + (ai * 2 + bj) * 16384), a1 = *(const GAS u32x4*)(Ga + (ai * 2 + bj) * 16384 + 16), b0 = *(const GAS u32x4*)(Gb + (ai * 2 + bj) * 16384), b1 = *(const GAS u32x4*)(Gb + (ai * 2 + bj) * 16384 + 16);
; #pragma unroll
.LBB0_655:
	s_lshl_b32 s16, s33, 2
	s_add_i32 s0, s16, -4
	s_cmp_lg_u32 s33, 0
	s_cselect_b32 s0, s0, 8
	s_ashr_i32 s1, s0, 31
	s_ashr_i32 s17, s86, 31
	s_add_u32 s18, s50, s86
	s_addc_u32 s9, s9, s17
	s_add_u32 s0, s18, s0
	s_addc_u32 s1, s9, s1
	s_lshl_b64 s[0:1], s[0:1], 16
	v_lshl_add_u64 v[128:129], v[202:203], 0, s[0:1]
	s_ashr_i32 s1, s16, 31
	s_add_u32 s0, s18, s16
	s_addc_u32 s1, s9, s1
	s_lshl_b64 s[0:1], s[0:1], 16
	v_lshl_add_u64 v[132:133], v[202:203], 0, s[0:1]
	s_movk_i32 s0, 0x4000
	v_add_co_u32_e32 v134, vcc, s0, v128
	s_mov_b64 s[16:17], 0x4000
	s_nop 0
	v_addc_co_u32_e32 v135, vcc, 0, v129, vcc
	global_load_dwordx4 v[176:179], v[128:129], off offset:16
	global_load_dwordx4 v[184:187], v[128:129], off
	global_load_dwordx4 v[180:183], v[132:133], off offset:16
	global_load_dwordx4 v[188:191], v[132:133], off
	v_lshl_add_u64 v[130:131], v[128:129], 0, s[16:17]
	global_load_dwordx4 v[168:171], v[134:135], off
	global_load_dwordx4 v[160:163], v[130:131], off offset:16
	v_add_co_u32_e32 v134, vcc, s0, v132
	v_lshl_add_u64 v[130:131], v[132:133], 0, s[16:17]
	s_nop 0
	v_addc_co_u32_e32 v135, vcc, 0, v133, vcc
	global_load_dwordx4 v[172:175], v[134:135], off
	global_load_dwordx4 v[164:167], v[130:131], off offset:16
	v_add_co_u32_e32 v134, vcc, s58, v128
	s_mov_b64 s[0:1], 0x8000
	s_nop 0
	v_addc_co_u32_e32 v135, vcc, 0, v129, vcc
	v_lshl_add_u64 v[130:131], v[128:129], 0, s[0:1]
	global_load_dwordx4 v[152:155], v[134:135], off
	global_load_dwordx4 v[144:147], v[130:131], off offset:16
	v_add_co_u32_e32 v134, vcc, s58, v132
	v_lshl_add_u64 v[130:131], v[132:133], 0, s[0:1]
	s_nop 0
	v_addc_co_u32_e32 v135, vcc, 0, v133, vcc
	s_mov_b64 s[0:1], 0xc000
	global_load_dwordx4 v[156:159], v[134:135], off
	global_load_dwordx4 v[148:151], v[130:131], off offset:16
	v_lshl_add_u64 v[130:131], v[128:129], 0, s[0:1]
	v_add_co_u32_e32 v128, vcc, 0xc000, v128
	v_lshl_add_u64 v[134:135], v[132:133], 0, s[0:1]
	s_nop 0
	v_addc_co_u32_e32 v129, vcc, 0, v129, vcc
	v_add_co_u32_e32 v132, vcc, 0xc000, v132
	global_load_dwordx4 v[136:139], v[128:129], off
	s_nop 0
	global_load_dwordx4 v[128:131], v[130:131], off offset:16
	v_addc_co_u32_e32 v133, vcc, 0, v133, vcc
	global_load_dwordx4 v[140:143], v[132:133], off
	s_nop 0
	global_load_dwordx4 v[132:135], v[134:135], off offset:16
	s_cmp_lg_u32 s33, 0
	s_cbranch_scc1 .Lsd2_done
	s_and_b64 vcc, exec, s[46:47]
	s_cbranch_vccnz .Lsd2_done
	v_readlane_b32 s90, v253, 3
	v_readlane_b32 s91, v253, 4
	s_cmp_lg_u64 s[90:91], 0
	s_cbranch_scc1 .Lsd2_done
	s_mov_b64 s[64:65], exec
	s_lshl_b32 s84, s23, 1
	s_add_u32 s90, s26, 0x6000
	s_addc_u32 s91, s27, 0
	s_add_u32 s90, s90, s84
	s_addc_u32 s91, s91, 0
	v_readlane_b32 s92, v254, 54
	s_mov_b32 exec_lo, -1
	s_mov_b32 exec_hi, 0
	s_add_i32 s92, s92, 2
	v_mbcnt_lo_u32_b32 v212, -1, 0
	v_lshlrev_b32_e32 v212, 2, v212
	v_mov_b32_e32 v213, s92
	s_mov_b32 s93, 0

; #define PG8_VOFF(vA, vB, hs, pit) do { _Pragma("unroll") for (int _i = 0; _i < 2; ++_i) { int R_, C_; stage_rc(tid * 16 + _i * 8192, R_, C_); vA[_i] = (unsigned)(R_ * (pit) + C_) * 2u; vB[_i] = (unsigned)(((R_ & ~31) + perm32(R_ & 31)) * (pit) + C_) * 2u; } hs = (size_t)HALF * (pit) * 2; } while (0)
; #define PG8_BAR __builtin_amdgcn_s_barrier()
; template <class Prog, bool ALIGN_EPI, bool NHALF = false, bool PITCHED = false, bool SLACK = false>
; __device__ __forceinline__ void gemm_phase(LAS unsigned char* lds, const int pitch, Prog& P, const int wave_, unsigned long long& t_k, unsigned long long& t_e) {
;     ...
;         if (!has_next) break;
;         if constexpr (Prog::HAS_MID) P.mid(acc, cur, wr, wc, fr, fq);
;         if constexpr (!Prog::HAS_MID)
; #pragma unroll
;         for (int a = 0; a < 2; ++a)
; #pragma unroll
;             for (int b = 0; b < (NHALF ? 1 : 2); ++b)
; #pragma unroll
;                 for (int m = 0; m < 4; ++m)
; #pragma unroll
;                     for (int n = 0; n < 2; ++n) acc[a][b][m][n] = (f32x4){0.f, 0.f, 0.f, 0.f};
;         if constexpr (SLACK) { P.next(ui + 1, cur); } else cur = nxt;
;         cA = nA; cB = nB; ++ui;
;         if constexpr (PITCHED) PG8_VOFF(voffA, voffB, hstep, cur.pitch);
;         if constexpr (ALIGN_EPI) { if (wr == 1) PG8_BAR; }
.Lsd2_done:
	s_nop 0
	s_nop 0
	s_andn2_b64 vcc, exec, s[28:29]
	s_cbranch_vccnz .LBB0_636
	s_barrier
	s_branch .LBB0_636
